# m1s
# speedup vs baseline: 1.0114x; 1.0114x over previous
; __global__ void __launch_bounds__(512, 2) fwd_megakernel(Params kp_) {
;     ...
;                                     for (int jb = 0; jb < ib; ++jb) {
;                                         float xj[16];
; #pragma unroll
;                                         for (int jj = 0; jj < 16; ++jj) xj[jj] = X[(jb * 16 + jj) * 128];
; #pragma unroll
;                                         for (int i = 0; i < 16; ++i) { const f32x4* lr = Ls4 + (ib * 16 + i) * 16 + jb * 4;
;                                             const f32x4 l0 = lr[0], l1 = lr[1], l2 = lr[2], l3 = lr[3];
;                                             r[i] -= ((l0.x * xj[0] + l0.y * xj[1]) + (l0.z * xj[2] + l0.w * xj[3])) + ((l1.x * xj[4] + l1.y * xj[5]) + (l1.z * xj[6] + l1.w * xj[7]))
;                                                   + ((l2.x * xj[8] + l2.y * xj[9]) + (l2.z * xj[10] + l2.w * xj[11])) + ((l3.x * xj[12] + l3.y * xj[13]) + (l3.z * xj[14] + l3.w * xj[15])); }
;                                     }
.LBB0_787:
	s_or_b64 exec, exec, s[18:19]
	s_cmp_lg_u32 s21, 0
	s_cbranch_scc0 .LBB0_754
	v_and_b32_e32 v0, 63, v199
	v_and_b32_e32 v1, 15, v0
	v_lshrrev_b32_e32 v2, 4, v0
	v_lshlrev_b32_e32 v3, 8, v1
	v_lshl_add_u32 v3, v2, 4, v3
	s_add_i32 s19, s20, 0x10000
	v_add_u32_e32 v3, s19, v3
	v_lshlrev_b32_e32 v4, 2, v0
	v_sub_u32_e32 v4, v104, v4
	v_lshl_add_u32 v4, v1, 4, v4
	v_lshl_add_u32 v4, v2, 11, v4
	v_bfe_u32 v5, v199, 6, 2
	v_lshlrev_b32_e32 v5, 12, v5
	v_add_u32_e32 v5, 0x18000, v5
	v_lshl_add_u32 v6, v0, 2, v5
	v_lshl_add_u32 v5, v2, 10, v5
	v_lshl_add_u32 v5, v1, 4, v5
	v_mov_b32_e32 v50, 0
	v_mov_b32_e32 v51, 0
	v_mov_b32_e32 v52, 0
	v_mov_b32_e32 v53, 0
	v_mov_b32_e32 v54, 0
	v_mov_b32_e32 v55, 0
	v_mov_b32_e32 v56, 0
	v_mov_b32_e32 v57, 0
	v_mov_b32_e32 v58, 0
	v_mov_b32_e32 v59, 0
	v_mov_b32_e32 v60, 0
	v_mov_b32_e32 v61, 0
	v_mov_b32_e32 v62, 0
	v_mov_b32_e32 v63, 0
	v_mov_b32_e32 v64, 0
	v_mov_b32_e32 v65, 0
	s_mov_b32 s18, 0
.Lm1s_jb:
	ds_read_b128 v[8:11], v3
	ds_read_b128 v[12:15], v4
	ds_read_b128 v[16:19], v4 offset:512
	ds_read_b128 v[20:23], v4 offset:1024
	ds_read_b128 v[24:27], v4 offset:1536
	s_waitcnt lgkmcnt(3)
	v_mfma_f32_16x16x4_f32 v[50:53], v8, v12, v[50:53]
	v_mfma_f32_16x16x4_f32 v[54:57], v8, v13, v[54:57]
	v_mfma_f32_16x16x4_f32 v[58:61], v8, v14, v[58:61]
	v_mfma_f32_16x16x4_f32 v[62:65], v8, v15, v[62:65]
	s_waitcnt lgkmcnt(2)
	v_mfma_f32_16x16x4_f32 v[50:53], v9, v16, v[50:53]
	v_mfma_f32_16x16x4_f32 v[54:57], v9, v17, v[54:57]
	v_mfma_f32_16x16x4_f32 v[58:61], v9, v18, v[58:61]
	v_mfma_f32_16x16x4_f32 v[62:65], v9, v19, v[62:65]
	s_waitcnt lgkmcnt(1)
	v_mfma_f32_16x16x4_f32 v[50:53], v10, v20, v[50:53]
	v_mfma_f32_16x16x4_f32 v[54:57], v10, v21, v[54:57]
	v_mfma_f32_16x16x4_f32 v[58:61], v10, v22, v[58:61]
	v_mfma_f32_16x16x4_f32 v[62:65], v10, v23, v[62:65]
	s_waitcnt lgkmcnt(0)
	v_mfma_f32_16x16x4_f32 v[50:53], v11, v24, v[50:53]
	v_mfma_f32_16x16x4_f32 v[54:57], v11, v25, v[54:57]
	v_mfma_f32_16x16x4_f32 v[58:61], v11, v26, v[58:61]
	v_mfma_f32_16x16x4_f32 v[62:65], v11, v27, v[62:65]
	v_add_u32_e32 v3, 64, v3
	v_add_u32_e32 v4, 0x2000, v4
	s_add_i32 s18, s18, 64
	s_cmp_eq_u32 s3, s18
	s_cbranch_scc0 .Lm1s_jb
	s_nop 7
	s_nop 3
	ds_write_b32 v5, v50
	ds_write_b32 v5, v51 offset:256
	ds_write_b32 v5, v52 offset:512
	ds_write_b32 v5, v53 offset:768
	ds_write_b32 v5, v54 offset:4
	ds_write_b32 v5, v55 offset:260
	ds_write_b32 v5, v56 offset:516
	ds_write_b32 v5, v57 offset:772
	ds_write_b32 v5, v58 offset:8
	ds_write_b32 v5, v59 offset:264
	ds_write_b32 v5, v60 offset:520
	ds_write_b32 v5, v61 offset:776
	ds_write_b32 v5, v62 offset:12
	ds_write_b32 v5, v63 offset:268
	ds_write_b32 v5, v64 offset:524
	ds_write_b32 v5, v65 offset:780
	ds_read2st64_b32 v[12:13], v6 offset1:1
	ds_read2st64_b32 v[14:15], v6 offset0:2 offset1:3
	ds_read2st64_b32 v[16:17], v6 offset0:4 offset1:5
	ds_read2st64_b32 v[18:19], v6 offset0:6 offset1:7
	ds_read2st64_b32 v[20:21], v6 offset0:8 offset1:9
	ds_read2st64_b32 v[22:23], v6 offset0:10 offset1:11
	ds_read2st64_b32 v[24:25], v6 offset0:12 offset1:13
	ds_read2st64_b32 v[26:27], v6 offset0:14 offset1:15
	s_waitcnt lgkmcnt(0)
	v_pk_add_f32 v[34:35], v[34:35], v[12:13] neg_lo:[0,1] neg_hi:[0,1]
	v_pk_add_f32 v[36:37], v[36:37], v[14:15] neg_lo:[0,1] neg_hi:[0,1]
	v_pk_add_f32 v[38:39], v[38:39], v[16:17] neg_lo:[0,1] neg_hi:[0,1]
	v_pk_add_f32 v[40:41], v[40:41], v[18:19] neg_lo:[0,1] neg_hi:[0,1]
	v_pk_add_f32 v[42:43], v[42:43], v[20:21] neg_lo:[0,1] neg_hi:[0,1]
	v_pk_add_f32 v[44:45], v[44:45], v[22:23] neg_lo:[0,1] neg_hi:[0,1]
	v_pk_add_f32 v[46:47], v[46:47], v[24:25] neg_lo:[0,1] neg_hi:[0,1]
	v_pk_add_f32 v[48:49], v[48:49], v[26:27] neg_lo:[0,1] neg_hi:[0,1]
	s_branch .LBB0_754
